# adds: mLSTM v^T staging writes remapped so a wave covers 32 token pairs (2 lanes per LDS bank instead of 8)
# baseline (speedup 1.0000x reference)
.LBB0_360:
	s_or_b64 exec, exec, s[0:1]
	s_lshl_b32 s0, s96, 2
	s_and_b32 s0, s0, 28
	s_ashr_i32 s1, s96, 5
	s_add_i32 s0, s0, s1
	s_ashr_i32 s6, s0, 2
	s_and_b32 s23, s1, 3
	s_bfe_u32 s41, s96, 0x20003
	s_add_u32 s64, s8, 0x1b36e000
	s_addc_u32 s65, s9, 0
	s_add_u32 s12, s8, 0x1f56e000
	s_addc_u32 s13, s9, 0
	s_ashr_i32 s7, s6, 31
	s_lshl_b32 s5, s41, 6
	s_ashr_i32 s40, s22, 6
	v_ashrrev_i32_e32 v3, 3, v2
	s_add_u32 s20, s8, 0xcc6e000
	v_and_b32_e32 v4, -4, v3
	s_addc_u32 s21, s9, 0
	s_lshl_b64 s[6:7], s[6:7], 11
	v_ashrrev_i32_e32 v5, 31, v4
	v_lshl_add_u64 v[4:5], s[6:7], 0, v[4:5]
	v_lshlrev_b64 v[4:5], 12, v[4:5]
	v_lshl_add_u64 v[4:5], s[64:65], 0, v[4:5]
	s_lshl_b32 s2, s23, 9
	s_waitcnt vmcnt(0)
	v_lshlrev_b32_e32 v26, 4, v2
	v_lshl_add_u64 v[4:5], v[4:5], 0, s[2:3]
	v_and_b32_e32 v158, 0x1f0, v26
	v_lshl_add_u64 v[16:17], v[4:5], 0, v[158:159]
	s_movk_i32 s10, 0x1000
	v_add_co_u32_e32 v18, vcc, s10, v16
	v_lshrrev_b32_e32 v3, 2, v2
	s_nop 0
	v_addc_co_u32_e32 v19, vcc, 0, v17, vcc
	s_movk_i32 s10, 0x2000
	v_and_or_b32 v22, v2, 62, s6
	v_mov_b32_e32 v23, s7
	v_add_co_u32_e32 v20, vcc, s10, v16
	v_lshlrev_b64 v[24:25], 11, v[22:23]
	s_nop 0
	v_addc_co_u32_e32 v21, vcc, 0, v17, vcc
	s_movk_i32 s10, 0x3000
	v_lshl_add_u64 v[24:25], s[20:21], 0, v[24:25]
	global_load_dwordx4 v[4:7], v[16:17], off
	global_load_dwordx4 v[88:91], v[16:17], off offset:2048
	global_load_dwordx4 v[8:11], v[20:21], off offset:-4096
	global_load_dwordx4 v[12:15], v[20:21], off
	global_load_dwordx4 v[92:95], v[20:21], off offset:2048
	v_add_co_u32_e32 v20, vcc, s10, v16
	v_lshl_add_u64 v[24:25], v[24:25], 0, s[2:3]
	s_lshl_b32 s36, s41, 7
	s_mov_b32 s37, s3
	v_addc_co_u32_e32 v21, vcc, 0, v17, vcc
	v_lshl_add_u64 v[24:25], v[24:25], 0, s[36:37]
	v_lshrrev_b32_e32 v158, 1, v2
	v_and_b32_e32 v158, 0x60, v158
	v_and_b32_e32 v214, 1, v2
	v_lshl_or_b32 v158, v214, 4, v158
	v_and_or_b32 v22, v2, 63, s6
	global_load_dwordx4 v[96:99], v[18:19], off offset:2048
	s_nop 0
	global_load_dwordx4 v[16:19], v[20:21], off
	v_lshl_add_u64 v[28:29], v[24:25], 0, v[158:159]
	global_load_dwordx4 v[100:103], v[20:21], off offset:2048
	global_load_dwordx4 v[24:27], v[28:29], off
	v_lshlrev_b64 v[20:21], 6, v[22:23]
	v_lshl_add_u64 v[20:21], s[12:13], 0, v[20:21]
	s_lshl_b32 s30, s23, 4
	s_mov_b32 s31, s3
	v_lshl_add_u64 v[20:21], v[20:21], 0, s[30:31]
	global_load_dwordx4 v[28:31], v[28:29], off offset:2048
	s_nop 0
	global_load_dwordx4 v[20:23], v[20:21], off
	s_lshl_b32 s4, s40, 5
	s_cmp_lt_i32 s40, 4
	s_cselect_b64 s[10:11], -1, 0
	s_cmp_lt_i32 s40, 2
	s_cselect_b64 s[34:35], -1, 0
	s_lshl_b32 s97, s40, 1
	s_add_i32 s31, s97, -8
	s_add_i32 s37, s40, 8
	v_cndmask_b32_e64 v32, 0, 1, s[34:35]
	s_cmp_gt_i32 s40, 3
	v_readfirstlane_b32 s34, v32
	s_cselect_b32 s93, 2, s34
	s_cselect_b32 s92, s31, s37
	s_add_u32 s12, s12, s30
	s_addc_u32 s13, s13, 0
	s_add_u32 s20, s20, s2
	s_addc_u32 s21, s21, 0
	s_add_u32 s30, s20, s36
	s_addc_u32 s31, s21, 0
	s_cmp_lt_u32 s22, 64
	s_cselect_b64 s[34:35], -1, 0
	s_cmp_lg_u32 s93, 0
	s_cselect_b64 s[38:39], -1, 0
	s_ashr_i32 s20, s22, 8
	s_lshl_b32 s21, s40, 4
	s_and_b32 s21, s21, 48
	s_lshl_b32 s40, s20, 4
	s_lshl_b32 s23, s23, 2
	s_add_u32 s23, s8, s23
	s_addc_u32 s37, s9, 0
	s_add_u32 s42, s23, 0x272c000
	s_addc_u32 s43, s37, 0
	s_add_u32 s8, s8, s2
	s_addc_u32 s9, s9, 0
	s_add_u32 s8, s8, s36
	s_addc_u32 s9, s9, 0
	s_add_u32 s44, s8, 0x1926e000
	s_addc_u32 s45, s9, 0
	s_cmp_eq_u32 s41, 0
	s_cselect_b64 s[8:9], -1, 0
	s_andn2_b32 s22, s22, 63
	s_add_i32 s22, s22, 0
	s_add_i32 s22, s22, 0x16500
	s_add_i32 s23, s40, 32
	s_cmp_gt_i32 s20, 3
	s_cselect_b64 s[48:49], -1, 0
	s_ashr_i32 s41, s40, 31
	s_cmp_gt_i32 s20, 1
	s_cselect_b64 s[50:51], -1, 0
	s_cmp_gt_i32 s20, -1
	s_cselect_b64 s[56:57], -1, 0
	s_add_u32 s64, s64, s2
	s_addc_u32 s65, s65, 0
	s_lshl_b32 s2, s92, 5
	s_mul_i32 s46, s92, 0x2100
	s_mov_b32 s1, 0
	s_add_i32 s2, s2, 0x14100
	s_lshl_b32 s36, s92, 6
	s_lshl_b32 s37, s92, 4
	s_add_i32 s46, s46, 0x8400
	s_waitcnt lgkmcnt(0)
	v_mov_b32_e32 v104, 0
	v_mov_b32_e32 v68, 0
	v_mov_b32_e32 v69, 0
	v_mov_b32_e32 v70, 0
	v_mov_b32_e32 v71, 0
	v_mov_b32_e32 v64, 0
	v_mov_b32_e32 v65, 0
	v_mov_b32_e32 v66, 0
	v_mov_b32_e32 v67, 0
	v_mov_b32_e32 v60, 0
	v_mov_b32_e32 v61, 0
	v_mov_b32_e32 v62, 0
	v_mov_b32_e32 v63, 0
	v_mov_b32_e32 v56, 0
	v_mov_b32_e32 v57, 0
	v_mov_b32_e32 v58, 0
	v_mov_b32_e32 v59, 0
	v_mov_b32_e32 v52, 0
	v_mov_b32_e32 v53, 0
	v_mov_b32_e32 v54, 0
	v_mov_b32_e32 v55, 0
	v_mov_b32_e32 v48, 0
	v_mov_b32_e32 v49, 0
	v_mov_b32_e32 v50, 0
	v_mov_b32_e32 v51, 0
	v_mov_b32_e32 v44, 0
	v_mov_b32_e32 v45, 0
	v_mov_b32_e32 v46, 0
	v_mov_b32_e32 v47, 0
	v_mov_b32_e32 v40, 0
	v_mov_b32_e32 v41, 0
	v_mov_b32_e32 v42, 0
	v_mov_b32_e32 v43, 0
	v_mov_b32_e32 v36, 0
	v_mov_b32_e32 v37, 0
	v_mov_b32_e32 v38, 0
	v_mov_b32_e32 v39, 0
	v_mov_b32_e32 v32, 0
	v_mov_b32_e32 v33, 0
	v_mov_b32_e32 v34, 0
	v_mov_b32_e32 v35, 0
	v_ashrrev_i32_e32 v214, 3, v2
	v_and_b32_e32 v214, -4, v214
	v_lshlrev_b32_e32 v215, 3, v2
	v_and_b32_e32 v215, 0xf8, v215
	v_lshlrev_b32_e32 v215, 1, v215
	v_lshl_add_u32 v214, v214, 12, v215
	v_add_u32_e32 v215, 0x3000, v214
	v_add_u32_e32 v214, 0x1000, v214
	v_lshrrev_b32_e32 v217, 1, v2
	v_and_b32_e32 v217, 0x60, v217
	v_and_b32_e32 v216, 1, v2
	v_lshl_or_b32 v217, v216, 4, v217
	v_bfe_u32 v216, v2, 1, 5
	v_lshlrev_b32_e32 v218, 2, v216
	v_lshl_add_u32 v216, v216, 12, v217
	v_lshrrev_b32_e32 v217, 4, v217
	v_mul_u32_u24_e32 v217, 0x480, v217
	v_add3_u32 v218, s86, v217, v218
	v_and_b32_e32 v217, 63, v2
	v_lshlrev_b32_e32 v217, 6, v217
	s_add_u32 s28, s6, 64
	s_addc_u32 s29, s7, 0
	s_lshl_b64 s[18:19], s[28:29], 12
	s_add_u32 s18, s18, s64
	s_addc_u32 s19, s19, s65
	s_lshl_b64 s[26:27], s[28:29], 11
	s_add_u32 s26, s26, s30
	s_addc_u32 s27, s27, s31
	s_lshl_b64 s[28:29], s[28:29], 6
	s_add_u32 s28, s28, s12
	s_addc_u32 s29, s29, s13
	s_and_b32 s15, s34, 31
	s_cmp_eq_u32 s20, 0
	s_cselect_b32 s32, 31, 0
	s_waitcnt vmcnt(0)

.LBB0_365:
	v_lshlrev_b32_e32 v72, 3, v163
	v_ashrrev_i32_e32 v165, 3, v163
	v_and_b32_e32 v164, 0xf8, v72
	v_and_b32_e32 v160, -4, v165
	v_lshl_add_u32 v72, v164, 1, 0
	v_mad_u64_u32 v[74:75], s[66:67], v160, s91, v[72:73]
	v_or_b32_e32 v73, 3, v165
	s_movk_i32 s47, 0x100
	s_waitcnt lgkmcnt(0)
	v_and_b32_e32 v104, 7, v163
	v_bfe_u32 v106, v163, 3, 5
	v_mad_u64_u32 v[72:73], s[66:67], v73, s91, v[72:73]
	v_cmp_gt_i32_e32 vcc, s47, v163
	ds_write_b128 v74, v[4:7]
	ds_write_b128 v74, v[88:91] offset:33792
	ds_write_b128 v74, v[8:11] offset:528
	ds_write_b128 v74, v[96:99] offset:34320
	ds_write_b128 v74, v[12:15] offset:1056
	ds_write_b128 v74, v[92:95] offset:34848
	ds_write_b128 v72, v[16:19]
	ds_write_b128 v72, v[100:103] offset:33792
	s_and_saveexec_b64 s[66:67], vcc
	s_cbranch_execz .LBB0_367
	v_and_b32_e32 v72, 0xffff, v24
	v_mov_b32_e32 v73, v218
	v_lshrrev_b32_e32 v74, 16, v24
	v_lshl_or_b32 v72, v28, 16, v72
	v_and_or_b32 v74, v28, s94, v74
	ds_write2_b32 v73, v72, v74 offset1:36
	v_and_b32_e32 v72, 0xffff, v25
	v_lshrrev_b32_e32 v74, 16, v25
	v_lshl_or_b32 v72, v29, 16, v72
	v_and_or_b32 v74, v29, s94, v74
	ds_write2_b32 v73, v72, v74 offset0:72 offset1:108
	v_and_b32_e32 v72, 0xffff, v26
	v_lshrrev_b32_e32 v74, 16, v26
	v_lshl_or_b32 v72, v30, 16, v72
	v_and_or_b32 v74, v30, s94, v74
	ds_write2_b32 v73, v72, v74 offset0:144 offset1:180
	v_and_b32_e32 v72, 0xffff, v27
	v_lshrrev_b32_e32 v74, 16, v27
	v_lshl_or_b32 v72, v31, 16, v72
	v_and_or_b32 v74, v31, s94, v74
	ds_write2_b32 v73, v72, v74 offset0:216 offset1:252
